# norm phases: all 16 loads of a row issued up front (counted waits); up1/up2 conversion loops de-serialized; scan via LDS-DMA; weight conversion in idle GEMM tails
# speedup vs baseline: 1.0411x; 1.0061x over previous
.LBB0_77:
	global_load_dwordx4 v[8:11], v[26:27], off offset:16
	global_load_dwordx4 v[12:15], v[26:27], off
	global_load_dwordx4 v[4:7], v[26:27], off offset:2048
	global_load_dwordx4 v[0:3], v[26:27], off offset:2064
	v_lshl_add_u64 v[26:27], v[26:27], 0, s[12:13]
	v_ashrrev_i32_e32 v30, 11, v16
	v_mul_hi_i32_i24_e32 v31, 0x2400, v30
	v_mul_i32_i24_e32 v30, 0x2400, v30
	v_lshlrev_b64 v[30:31], 2, v[30:31]
	v_lshl_add_u64 v[32:33], v[22:23], 0, v[30:31]
	v_lshl_add_u64 v[30:31], v[20:21], 0, v[30:31]
	global_load_dwordx4 v[36:39], v[18:19], off offset:16
	global_load_dwordx4 v[40:43], v[18:19], off
	global_load_dwordx4 v[44:47], v[32:33], off offset:16
	global_load_dwordx4 v[48:51], v[32:33], off
	global_load_dwordx4 v[52:55], v[30:31], off offset:16
	global_load_dwordx4 v[56:59], v[30:31], off
	global_load_dwordx4 v[60:63], v[18:19], off offset:2064
	global_load_dwordx4 v[64:67], v[18:19], off offset:2048
	global_load_dwordx4 v[68:71], v[32:33], off offset:2064
	global_load_dwordx4 v[72:75], v[32:33], off offset:2048
	global_load_dwordx4 v[76:79], v[30:31], off offset:2064
	global_load_dwordx4 v[80:83], v[30:31], off offset:2048
	s_waitcnt vmcnt(14)
	v_mul_f32_e32 v85, v9, v9
	s_waitcnt vmcnt(14)
	v_mul_f32_e32 v84, v13, v13
	v_fmac_f32_e32 v84, v12, v12
	v_fmac_f32_e32 v85, v8, v8
	v_fmac_f32_e32 v84, v14, v14
	v_fmac_f32_e32 v85, v10, v10
	v_fmac_f32_e32 v84, v15, v15
	v_fmac_f32_e32 v85, v11, v11
	v_add_f32_e32 v17, v84, v85
	s_waitcnt vmcnt(13)
	v_mov_b32_e32 v32, v5
	s_waitcnt vmcnt(12)
	v_mov_b32_e32 v33, v1
	v_mov_b32_e32 v30, v4
	v_mov_b32_e32 v31, v0
	v_pk_mul_f32 v[32:33], v[32:33], v[32:33]
	s_nop 0
	v_pk_fma_f32 v[30:31], v[30:31], v[30:31], v[32:33]
	v_mov_b32_e32 v32, v6
	v_mov_b32_e32 v33, v2
	v_pk_fma_f32 v[30:31], v[32:33], v[32:33], v[30:31]
	v_mov_b32_e32 v32, v7
	v_mov_b32_e32 v33, v3
	v_pk_fma_f32 v[30:31], v[32:33], v[32:33], v[30:31]
	s_nop 0
	v_add_f32_e32 v17, v17, v30
	v_add_f32_e32 v17, v17, v31
	s_nop 1
	v_add_f32_dpp v17, v17, v17 quad_perm:[1,0,3,2] row_mask:0xf bank_mask:0xf bound_ctrl:1
	v_add_u32_e32 v16, s20, v16
	v_cmp_lt_i32_e32 vcc, s8, v16
	v_add_f32_dpp v17, v17, v17 quad_perm:[2,3,0,1] row_mask:0xf bank_mask:0xf bound_ctrl:1
	s_or_b64 s[6:7], vcc, s[6:7]
	s_nop 0
	v_add_f32_dpp v17, v17, v17 row_half_mirror row_mask:0xf bank_mask:0xf bound_ctrl:1
	s_nop 1
	v_add_f32_dpp v17, v17, v17 row_mirror row_mask:0xf bank_mask:0xf bound_ctrl:1
	ds_bpermute_b32 v28, v29, v17
	s_waitcnt lgkmcnt(0)
	v_add_f32_e32 v17, v17, v28
	ds_bpermute_b32 v28, v34, v17
	s_waitcnt lgkmcnt(0)
	v_add_f32_e32 v17, v17, v28
	v_fmamk_f32 v17, v17, 0x3a800000, v155
	v_rsq_f32_e32 v28, v17
	s_nop 0
	v_pk_mul_f32 v[8:9], v[8:9], v[28:29] op_sel_hi:[1,0]
	v_pk_mul_f32 v[12:13], v[12:13], v[28:29] op_sel_hi:[1,0]
	v_pk_mul_f32 v[14:15], v[14:15], v[28:29] op_sel_hi:[1,0]
	v_pk_mul_f32 v[0:1], v[0:1], v[28:29] op_sel_hi:[1,0]
	v_pk_mul_f32 v[4:5], v[4:5], v[28:29] op_sel_hi:[1,0]
	v_pk_mul_f32 v[6:7], v[6:7], v[28:29] op_sel_hi:[1,0]
	s_waitcnt vmcnt(11)
	v_pk_mul_f32 v[8:9], v[36:37], v[8:9]
	s_waitcnt vmcnt(10)
	v_pk_mul_f32 v[12:13], v[40:41], v[12:13]
	s_waitcnt vmcnt(9)
	v_pk_add_f32 v[36:37], v[44:45], 1.0 op_sel_hi:[1,0]
	s_waitcnt vmcnt(8)
	v_pk_add_f32 v[40:41], v[48:49], 1.0 op_sel_hi:[1,0]
	s_waitcnt vmcnt(7)
	v_pk_fma_f32 v[36:37], v[36:37], v[8:9], v[52:53]
	v_pk_mul_f32 v[8:9], v[10:11], v[28:29] op_sel_hi:[1,0]
	s_waitcnt vmcnt(6)
	v_pk_fma_f32 v[12:13], v[40:41], v[12:13], v[56:57]
	v_pk_mul_f32 v[14:15], v[42:43], v[14:15]
	v_pk_add_f32 v[40:41], v[50:51], 1.0 op_sel_hi:[1,0]
	v_pk_mul_f32 v[8:9], v[38:39], v[8:9]
	v_pk_add_f32 v[10:11], v[46:47], 1.0 op_sel_hi:[1,0]
	v_pk_fma_f32 v[14:15], v[40:41], v[14:15], v[58:59]
	v_pk_fma_f32 v[38:39], v[10:11], v[8:9], v[54:55]
	v_cvt_pk_bf16_f32 v8, v12, v13
	v_cvt_pk_bf16_f32 v9, v14, v15
	v_cvt_pk_bf16_f32 v10, v36, v37
	v_cvt_pk_bf16_f32 v11, v38, v39
	global_store_dwordx4 v[24:25], v[8:11], off
	s_waitcnt vmcnt(6)
	v_pk_mul_f32 v[0:1], v[0:1], v[60:61]
	s_waitcnt vmcnt(5)
	v_pk_mul_f32 v[4:5], v[64:65], v[4:5]
	s_waitcnt vmcnt(4)
	v_pk_add_f32 v[60:61], v[68:69], 1.0 op_sel_hi:[1,0]
	s_waitcnt vmcnt(3)
	v_pk_add_f32 v[64:65], v[72:73], 1.0 op_sel_hi:[1,0]
	s_waitcnt vmcnt(2)
	v_pk_fma_f32 v[60:61], v[0:1], v[60:61], v[76:77]
	v_pk_mul_f32 v[0:1], v[2:3], v[28:29] op_sel_hi:[1,0]
	s_waitcnt vmcnt(1)
	v_pk_fma_f32 v[4:5], v[64:65], v[4:5], v[80:81]
	v_pk_mul_f32 v[6:7], v[66:67], v[6:7]
	v_pk_add_f32 v[64:65], v[74:75], 1.0 op_sel_hi:[1,0]
	v_pk_mul_f32 v[0:1], v[0:1], v[62:63]
	v_pk_add_f32 v[2:3], v[70:71], 1.0 op_sel_hi:[1,0]
	v_pk_fma_f32 v[6:7], v[64:65], v[6:7], v[82:83]
	v_pk_fma_f32 v[62:63], v[0:1], v[2:3], v[78:79]
	v_cvt_pk_bf16_f32 v0, v4, v5
	v_cvt_pk_bf16_f32 v1, v6, v7
	v_cvt_pk_bf16_f32 v2, v60, v61
	v_cvt_pk_bf16_f32 v3, v62, v63
	global_store_dwordx4 v[24:25], v[0:3], off offset:1024
	v_lshl_add_u64 v[24:25], v[24:25], 0, s[10:11]
	s_andn2_b64 exec, exec, s[6:7]
	s_cbranch_execnz .LBB0_77

.LBB0_188:
	global_load_dwordx4 v[8:11], v[26:27], off offset:16
	global_load_dwordx4 v[12:15], v[26:27], off
	global_load_dwordx4 v[4:7], v[26:27], off offset:2048
	global_load_dwordx4 v[0:3], v[26:27], off offset:2064
	v_lshl_add_u64 v[26:27], v[26:27], 0, s[10:11]
	v_ashrrev_i32_e32 v30, 11, v16
	v_mul_hi_i32_i24_e32 v31, 0x2400, v30
	v_mul_i32_i24_e32 v30, 0x2400, v30
	v_lshlrev_b64 v[30:31], 2, v[30:31]
	v_lshl_add_u64 v[32:33], v[20:21], 0, v[30:31]
	v_lshl_add_u64 v[30:31], v[22:23], 0, v[30:31]
	global_load_dwordx4 v[36:39], v[18:19], off offset:16
	global_load_dwordx4 v[40:43], v[18:19], off
	global_load_dwordx4 v[44:47], v[32:33], off offset:16
	global_load_dwordx4 v[48:51], v[32:33], off
	global_load_dwordx4 v[52:55], v[30:31], off offset:16
	global_load_dwordx4 v[56:59], v[30:31], off
	global_load_dwordx4 v[60:63], v[18:19], off offset:2064
	global_load_dwordx4 v[64:67], v[18:19], off offset:2048
	global_load_dwordx4 v[68:71], v[32:33], off offset:2064
	global_load_dwordx4 v[72:75], v[32:33], off offset:2048
	global_load_dwordx4 v[76:79], v[30:31], off offset:2064
	global_load_dwordx4 v[80:83], v[30:31], off offset:2048
	s_waitcnt vmcnt(14)
	v_mul_f32_e32 v85, v9, v9
	v_mul_f32_e32 v84, v13, v13
	v_fmac_f32_e32 v84, v12, v12
	v_fmac_f32_e32 v85, v8, v8
	v_fmac_f32_e32 v84, v14, v14
	v_fmac_f32_e32 v85, v10, v10
	v_fmac_f32_e32 v84, v15, v15
	v_fmac_f32_e32 v85, v11, v11
	v_add_f32_e32 v17, v84, v85
	s_waitcnt vmcnt(13)
	v_mov_b32_e32 v32, v5
	s_waitcnt vmcnt(12)
	v_mov_b32_e32 v33, v1
	v_mov_b32_e32 v30, v4
	v_mov_b32_e32 v31, v0
	v_pk_mul_f32 v[32:33], v[32:33], v[32:33]
	s_nop 0
	v_pk_fma_f32 v[30:31], v[30:31], v[30:31], v[32:33]
	v_mov_b32_e32 v32, v6
	v_mov_b32_e32 v33, v2
	v_pk_fma_f32 v[30:31], v[32:33], v[32:33], v[30:31]
	v_mov_b32_e32 v32, v7
	v_mov_b32_e32 v33, v3
	v_pk_fma_f32 v[30:31], v[32:33], v[32:33], v[30:31]
	s_nop 0
	v_add_f32_e32 v17, v17, v30
	v_add_f32_e32 v17, v17, v31
	s_nop 1
	v_add_f32_dpp v17, v17, v17 quad_perm:[1,0,3,2] row_mask:0xf bank_mask:0xf bound_ctrl:1
	v_add_u32_e32 v16, s20, v16
	v_cmp_lt_i32_e32 vcc, s6, v16
	v_add_f32_dpp v17, v17, v17 quad_perm:[2,3,0,1] row_mask:0xf bank_mask:0xf bound_ctrl:1
	s_or_b64 s[4:5], vcc, s[4:5]
	s_nop 0
	v_add_f32_dpp v17, v17, v17 row_half_mirror row_mask:0xf bank_mask:0xf bound_ctrl:1
	s_nop 1
	v_add_f32_dpp v17, v17, v17 row_mirror row_mask:0xf bank_mask:0xf bound_ctrl:1
	ds_bpermute_b32 v28, v29, v17
	s_waitcnt lgkmcnt(0)
	v_add_f32_e32 v17, v17, v28
	ds_bpermute_b32 v28, v34, v17
	s_waitcnt lgkmcnt(0)
	v_add_f32_e32 v17, v17, v28
	v_fmamk_f32 v17, v17, 0x3a800000, v155
	v_rsq_f32_e32 v28, v17
	s_nop 0
	v_pk_mul_f32 v[8:9], v[8:9], v[28:29] op_sel_hi:[1,0]
	v_pk_mul_f32 v[12:13], v[12:13], v[28:29] op_sel_hi:[1,0]
	v_pk_mul_f32 v[14:15], v[14:15], v[28:29] op_sel_hi:[1,0]
	v_pk_mul_f32 v[0:1], v[0:1], v[28:29] op_sel_hi:[1,0]
	v_pk_mul_f32 v[4:5], v[4:5], v[28:29] op_sel_hi:[1,0]
	v_pk_mul_f32 v[6:7], v[6:7], v[28:29] op_sel_hi:[1,0]
	s_waitcnt vmcnt(11)
	v_pk_mul_f32 v[8:9], v[36:37], v[8:9]
	s_waitcnt vmcnt(10)
	v_pk_mul_f32 v[12:13], v[40:41], v[12:13]
	s_waitcnt vmcnt(9)
	v_pk_add_f32 v[36:37], v[44:45], 1.0 op_sel_hi:[1,0]
	s_waitcnt vmcnt(8)
	v_pk_add_f32 v[40:41], v[48:49], 1.0 op_sel_hi:[1,0]
	s_waitcnt vmcnt(7)
	v_pk_fma_f32 v[36:37], v[36:37], v[8:9], v[52:53]
	v_pk_mul_f32 v[8:9], v[10:11], v[28:29] op_sel_hi:[1,0]
	s_waitcnt vmcnt(6)
	v_pk_fma_f32 v[12:13], v[40:41], v[12:13], v[56:57]
	v_pk_mul_f32 v[14:15], v[42:43], v[14:15]
	v_pk_add_f32 v[40:41], v[50:51], 1.0 op_sel_hi:[1,0]
	v_pk_mul_f32 v[8:9], v[38:39], v[8:9]
	v_pk_add_f32 v[10:11], v[46:47], 1.0 op_sel_hi:[1,0]
	v_pk_fma_f32 v[14:15], v[40:41], v[14:15], v[58:59]
	v_pk_fma_f32 v[38:39], v[10:11], v[8:9], v[54:55]
	v_cvt_pk_bf16_f32 v8, v12, v13
	v_cvt_pk_bf16_f32 v9, v14, v15
	v_cvt_pk_bf16_f32 v10, v36, v37
	v_cvt_pk_bf16_f32 v11, v38, v39
	global_store_dwordx4 v[24:25], v[8:11], off
	s_waitcnt vmcnt(6)
	v_pk_mul_f32 v[0:1], v[0:1], v[60:61]
	s_waitcnt vmcnt(5)
	v_pk_mul_f32 v[4:5], v[64:65], v[4:5]
	s_waitcnt vmcnt(4)
	v_pk_add_f32 v[60:61], v[68:69], 1.0 op_sel_hi:[1,0]
	s_waitcnt vmcnt(3)
	v_pk_add_f32 v[64:65], v[72:73], 1.0 op_sel_hi:[1,0]
	s_waitcnt vmcnt(2)
	v_pk_fma_f32 v[60:61], v[0:1], v[60:61], v[76:77]
	v_pk_mul_f32 v[0:1], v[2:3], v[28:29] op_sel_hi:[1,0]
	s_waitcnt vmcnt(1)
	v_pk_fma_f32 v[4:5], v[64:65], v[4:5], v[80:81]
	v_pk_mul_f32 v[6:7], v[66:67], v[6:7]
	v_pk_add_f32 v[64:65], v[74:75], 1.0 op_sel_hi:[1,0]
	v_pk_mul_f32 v[0:1], v[0:1], v[62:63]
	v_pk_add_f32 v[2:3], v[70:71], 1.0 op_sel_hi:[1,0]
	v_pk_fma_f32 v[6:7], v[64:65], v[6:7], v[82:83]
	v_pk_fma_f32 v[62:63], v[0:1], v[2:3], v[78:79]
	v_cvt_pk_bf16_f32 v0, v4, v5
	v_cvt_pk_bf16_f32 v1, v6, v7
	v_cvt_pk_bf16_f32 v2, v60, v61
	v_cvt_pk_bf16_f32 v3, v62, v63
	global_store_dwordx4 v[24:25], v[0:3], off offset:1024
	v_lshl_add_u64 v[24:25], v[24:25], 0, s[8:9]
	s_andn2_b64 exec, exec, s[4:5]
	s_cbranch_execnz .LBB0_188

.LBB0_433:
	s_ashr_i32 s0, s7, 31
	s_lshr_b32 s0, s0, 28
	s_add_i32 s0, s7, s0
	s_ashr_i32 s0, s0, 4
	s_bfe_i32 s10, s0, 0x10001
	s_lshl_b32 s11, s0, 5
	s_lshl_b32 s1, s0, 6
	s_and_b32 s10, s10, 0xb00
	s_and_b32 s11, s11, 0xffffff80
	s_add_i32 s10, s10, s11
	s_and_b32 s11, s1, 64
	s_lshl_b32 s0, s0, 10
	s_or_b32 s10, s10, s11
	s_sub_i32 s15, s6, s0
	s_ashr_i32 s11, s10, 31
	v_add_u32_e32 v18, s15, v4
	v_lshl_add_u64 v[16:17], s[10:11], 2, v[0:1]
	v_add_u32_e32 v12, 0xffffc000, v18
	v_mad_i64_i32 v[12:13], s[10:11], v12, s27, v[16:17]
	global_load_dwordx4 v[12:15], v[12:13], off nt
	v_add_u32_e32 v40, 0xffffc010, v18
	v_mad_i64_i32 v[40:41], s[10:11], v40, s27, v[16:17]
	global_load_dwordx4 v[40:43], v[40:41], off nt
	v_add_u32_e32 v44, 0xffffc020, v18
	v_mad_i64_i32 v[44:45], s[10:11], v44, s27, v[16:17]
	global_load_dwordx4 v[44:47], v[44:45], off nt
	v_add_u32_e32 v48, 0xffffc030, v18
	v_mad_i64_i32 v[48:49], s[10:11], v48, s27, v[16:17]
	global_load_dwordx4 v[48:51], v[48:49], off nt
	s_add_i32 s0, s15, 0xffffc000
	s_add_i32 s7, s7, s23
	s_add_i32 s6, s6, s26
	v_add_u32_e32 v17, 0x400, v11
	v_or_b32_e32 v16, s1, v5
	s_ashr_i32 s1, s0, 31
	v_lshl_add_u64 v[18:19], s[0:1], 1, v[2:3]
	s_cmpk_lt_i32 s7, 0x580
	s_waitcnt vmcnt(3)
	ds_write2_b32 v7, v12, v13 offset1:1
	ds_write2_b32 v7, v14, v15 offset0:2 offset1:3
	s_waitcnt vmcnt(2)
	ds_write2_b32 v8, v40, v41 offset1:1
	ds_write2_b32 v8, v42, v43 offset0:2 offset1:3
	s_waitcnt vmcnt(1)
	ds_write2_b32 v9, v44, v45 offset1:1
	ds_write2_b32 v9, v46, v47 offset0:2 offset1:3
	s_waitcnt vmcnt(0)
	ds_write2_b32 v10, v48, v49 offset1:1
	ds_write2_b32 v10, v50, v51 offset0:2 offset1:3
	v_add_u32_e32 v14, 0x200, v11
	s_waitcnt lgkmcnt(0)
	s_barrier
	ds_read2_b32 v[20:21], v6 offset1:32
	ds_read2_b32 v[12:13], v11 offset0:65 offset1:130
	ds_read2_b32 v[14:15], v14 offset0:67 offset1:132
	ds_read2_b32 v[22:23], v17 offset0:69 offset1:134
	ds_read_b32 v17, v11 offset:1820
	s_waitcnt lgkmcnt(3)
	v_cvt_pk_bf16_f32 v12, v20, v12
	s_waitcnt lgkmcnt(2)
	v_cvt_pk_bf16_f32 v13, v13, v14
	s_waitcnt lgkmcnt(1)
	v_cvt_pk_bf16_f32 v14, v15, v22
	s_waitcnt lgkmcnt(0)
	v_cvt_pk_bf16_f32 v15, v23, v17
	v_ashrrev_i32_e32 v17, 31, v16
	v_lshlrev_b64 v[22:23], 11, v[16:17]
	v_lshl_add_u64 v[22:23], v[18:19], 0, v[22:23]
	global_store_dwordx4 v[22:23], v[12:15], off
	v_add_u32_e32 v17, 0x400, v6
	ds_read2_b32 v[12:13], v6 offset0:97 offset1:162
	v_add_u32_e32 v14, 0x200, v6
	ds_read2_b32 v[14:15], v14 offset0:99 offset1:164
	ds_read2_b32 v[22:23], v17 offset0:101 offset1:166
	ds_read_b32 v17, v6 offset:1948
	v_or_b32_e32 v16, 32, v16
	s_waitcnt lgkmcnt(3)
	v_cvt_pk_bf16_f32 v12, v21, v12
	s_waitcnt lgkmcnt(2)
	v_cvt_pk_bf16_f32 v13, v13, v14
	s_waitcnt lgkmcnt(1)
	v_cvt_pk_bf16_f32 v14, v15, v22
	s_waitcnt lgkmcnt(0)
	v_cvt_pk_bf16_f32 v15, v23, v17
	v_ashrrev_i32_e32 v17, 31, v16
	v_lshlrev_b64 v[16:17], 11, v[16:17]
	v_lshl_add_u64 v[16:17], v[18:19], 0, v[16:17]
	global_store_dwordx4 v[16:17], v[12:15], off
	s_barrier
	s_cbranch_scc1 .LBB0_433

.LBB0_460:
	s_ashr_i32 s0, s5, 31
	s_lshr_b32 s0, s0, 28
	s_add_i32 s0, s5, s0
	s_ashr_i32 s0, s0, 4
	s_bfe_i32 s8, s0, 0x10001
	s_lshl_b32 s9, s0, 5
	s_lshl_b32 s1, s0, 6
	s_and_b32 s8, s8, 0xb00
	s_and_b32 s9, s9, 0xffffff80
	s_add_i32 s8, s8, s9
	s_and_b32 s9, s1, 64
	s_lshl_b32 s0, s0, 10
	s_or_b32 s8, s8, s9
	s_sub_i32 s14, s4, s0
	s_ashr_i32 s9, s8, 31
	v_add_u32_e32 v18, s14, v4
	v_lshl_add_u64 v[16:17], s[8:9], 2, v[0:1]
	v_add_u32_e32 v12, 0xffffc000, v18
	v_mad_i64_i32 v[12:13], s[8:9], v12, s26, v[16:17]
	global_load_dwordx4 v[12:15], v[12:13], off nt
	v_add_u32_e32 v40, 0xffffc010, v18
	v_mad_i64_i32 v[40:41], s[8:9], v40, s26, v[16:17]
	global_load_dwordx4 v[40:43], v[40:41], off nt
	v_add_u32_e32 v44, 0xffffc020, v18
	v_mad_i64_i32 v[44:45], s[8:9], v44, s26, v[16:17]
	global_load_dwordx4 v[44:47], v[44:45], off nt
	v_add_u32_e32 v48, 0xffffc030, v18
	v_mad_i64_i32 v[48:49], s[8:9], v48, s26, v[16:17]
	global_load_dwordx4 v[48:51], v[48:49], off nt
	s_add_i32 s0, s14, 0xffffc000
	s_add_i32 s5, s5, s15
	s_add_i32 s4, s4, s23
	v_add_u32_e32 v17, 0x400, v11
	v_or_b32_e32 v16, s1, v5
	s_ashr_i32 s1, s0, 31
	v_lshl_add_u64 v[18:19], s[0:1], 1, v[2:3]
	s_cmpk_lt_i32 s5, 0x580
	s_waitcnt vmcnt(3)
	ds_write2_b32 v7, v12, v13 offset1:1
	ds_write2_b32 v7, v14, v15 offset0:2 offset1:3
	s_waitcnt vmcnt(2)
	ds_write2_b32 v8, v40, v41 offset1:1
	ds_write2_b32 v8, v42, v43 offset0:2 offset1:3
	s_waitcnt vmcnt(1)
	ds_write2_b32 v9, v44, v45 offset1:1
	ds_write2_b32 v9, v46, v47 offset0:2 offset1:3
	s_waitcnt vmcnt(0)
	ds_write2_b32 v10, v48, v49 offset1:1
	ds_write2_b32 v10, v50, v51 offset0:2 offset1:3
	v_add_u32_e32 v14, 0x200, v11
	s_waitcnt lgkmcnt(0)
	s_barrier
	ds_read2_b32 v[20:21], v6 offset1:32
	ds_read2_b32 v[12:13], v11 offset0:65 offset1:130
	ds_read2_b32 v[14:15], v14 offset0:67 offset1:132
	ds_read2_b32 v[22:23], v17 offset0:69 offset1:134
	ds_read_b32 v17, v11 offset:1820
	s_waitcnt lgkmcnt(3)
	v_cvt_pk_bf16_f32 v12, v20, v12
	s_waitcnt lgkmcnt(2)
	v_cvt_pk_bf16_f32 v13, v13, v14
	s_waitcnt lgkmcnt(1)
	v_cvt_pk_bf16_f32 v14, v15, v22
	s_waitcnt lgkmcnt(0)
	v_cvt_pk_bf16_f32 v15, v23, v17
	v_ashrrev_i32_e32 v17, 31, v16
	v_lshlrev_b64 v[22:23], 11, v[16:17]
	v_lshl_add_u64 v[22:23], v[18:19], 0, v[22:23]
	global_store_dwordx4 v[22:23], v[12:15], off
	v_add_u32_e32 v17, 0x400, v6
	ds_read2_b32 v[12:13], v6 offset0:97 offset1:162
	v_add_u32_e32 v14, 0x200, v6
	ds_read2_b32 v[14:15], v14 offset0:99 offset1:164
	ds_read2_b32 v[22:23], v17 offset0:101 offset1:166
	ds_read_b32 v17, v6 offset:1948
	v_or_b32_e32 v16, 32, v16
	s_waitcnt lgkmcnt(3)
	v_cvt_pk_bf16_f32 v12, v21, v12
	s_waitcnt lgkmcnt(2)
	v_cvt_pk_bf16_f32 v13, v13, v14
	s_waitcnt lgkmcnt(1)
	v_cvt_pk_bf16_f32 v14, v15, v22
	s_waitcnt lgkmcnt(0)
	v_cvt_pk_bf16_f32 v15, v23, v17
	v_ashrrev_i32_e32 v17, 31, v16
	v_lshlrev_b64 v[16:17], 11, v[16:17]
	v_lshl_add_u64 v[16:17], v[18:19], 0, v[16:17]
	global_store_dwordx4 v[16:17], v[12:15], off
	s_barrier
	s_cbranch_scc1 .LBB0_460

.LBB0_626:
	global_load_dwordx4 v[8:11], v[26:27], off offset:16
	global_load_dwordx4 v[12:15], v[26:27], off
	global_load_dwordx4 v[4:7], v[26:27], off offset:2048
	global_load_dwordx4 v[0:3], v[26:27], off offset:2064
	v_lshl_add_u64 v[26:27], v[26:27], 0, s[36:37]
	v_ashrrev_i32_e32 v30, 11, v16
	v_mul_hi_i32_i24_e32 v31, 0x2400, v30
	v_mul_i32_i24_e32 v30, 0x2400, v30
	v_lshlrev_b64 v[30:31], 2, v[30:31]
	v_lshl_add_u64 v[32:33], v[20:21], 0, v[30:31]
	v_lshl_add_u64 v[30:31], v[22:23], 0, v[30:31]
	global_load_dwordx4 v[36:39], v[18:19], off offset:16
	global_load_dwordx4 v[40:43], v[18:19], off
	global_load_dwordx4 v[44:47], v[32:33], off offset:16
	global_load_dwordx4 v[48:51], v[32:33], off
	global_load_dwordx4 v[52:55], v[30:31], off offset:16
	global_load_dwordx4 v[56:59], v[30:31], off
	global_load_dwordx4 v[60:63], v[18:19], off offset:2064
	global_load_dwordx4 v[64:67], v[18:19], off offset:2048
	global_load_dwordx4 v[68:71], v[32:33], off offset:2064
	global_load_dwordx4 v[72:75], v[32:33], off offset:2048
	global_load_dwordx4 v[76:79], v[30:31], off offset:2064
	global_load_dwordx4 v[80:83], v[30:31], off offset:2048
	s_waitcnt vmcnt(14)
	v_mul_f32_e32 v85, v9, v9
	v_mul_f32_e32 v84, v13, v13
	v_fmac_f32_e32 v84, v12, v12
	v_fmac_f32_e32 v85, v8, v8
	v_fmac_f32_e32 v84, v14, v14
	v_fmac_f32_e32 v85, v10, v10
	v_fmac_f32_e32 v84, v15, v15
	v_fmac_f32_e32 v85, v11, v11
	v_add_f32_e32 v17, v84, v85
	s_waitcnt vmcnt(13)
	v_mov_b32_e32 v32, v5
	s_waitcnt vmcnt(12)
	v_mov_b32_e32 v33, v1
	v_mov_b32_e32 v30, v4
	v_mov_b32_e32 v31, v0
	v_pk_mul_f32 v[32:33], v[32:33], v[32:33]
	s_nop 0
	v_pk_fma_f32 v[30:31], v[30:31], v[30:31], v[32:33]
	v_mov_b32_e32 v32, v6
	v_mov_b32_e32 v33, v2
	v_pk_fma_f32 v[30:31], v[32:33], v[32:33], v[30:31]
	v_mov_b32_e32 v32, v7
	v_mov_b32_e32 v33, v3
	v_pk_fma_f32 v[30:31], v[32:33], v[32:33], v[30:31]
	s_nop 0
	v_add_f32_e32 v17, v17, v30
	v_add_f32_e32 v17, v17, v31
	s_nop 1
	v_add_f32_dpp v17, v17, v17 quad_perm:[1,0,3,2] row_mask:0xf bank_mask:0xf bound_ctrl:1
	v_add_u32_e32 v16, s20, v16
	v_cmp_lt_i32_e32 vcc, s6, v16
	v_add_f32_dpp v17, v17, v17 quad_perm:[2,3,0,1] row_mask:0xf bank_mask:0xf bound_ctrl:1
	s_or_b64 s[4:5], vcc, s[4:5]
	s_nop 0
	v_add_f32_dpp v17, v17, v17 row_half_mirror row_mask:0xf bank_mask:0xf bound_ctrl:1
	s_nop 1
	v_add_f32_dpp v17, v17, v17 row_mirror row_mask:0xf bank_mask:0xf bound_ctrl:1
	ds_bpermute_b32 v28, v29, v17
	s_waitcnt lgkmcnt(0)
	v_add_f32_e32 v17, v17, v28
	ds_bpermute_b32 v28, v34, v17
	s_waitcnt lgkmcnt(0)
	v_add_f32_e32 v17, v17, v28
	v_fmamk_f32 v17, v17, 0x3a800000, v155
	v_rsq_f32_e32 v28, v17
	s_nop 0
	v_pk_mul_f32 v[8:9], v[8:9], v[28:29] op_sel_hi:[1,0]
	v_pk_mul_f32 v[12:13], v[12:13], v[28:29] op_sel_hi:[1,0]
	v_pk_mul_f32 v[14:15], v[14:15], v[28:29] op_sel_hi:[1,0]
	v_pk_mul_f32 v[0:1], v[0:1], v[28:29] op_sel_hi:[1,0]
	v_pk_mul_f32 v[4:5], v[4:5], v[28:29] op_sel_hi:[1,0]
	v_pk_mul_f32 v[6:7], v[6:7], v[28:29] op_sel_hi:[1,0]
	s_waitcnt vmcnt(11)
	v_pk_mul_f32 v[8:9], v[36:37], v[8:9]
	s_waitcnt vmcnt(10)
	v_pk_mul_f32 v[12:13], v[40:41], v[12:13]
	s_waitcnt vmcnt(9)
	v_pk_add_f32 v[36:37], v[44:45], 1.0 op_sel_hi:[1,0]
	s_waitcnt vmcnt(8)
	v_pk_add_f32 v[40:41], v[48:49], 1.0 op_sel_hi:[1,0]
	s_waitcnt vmcnt(7)
	v_pk_fma_f32 v[36:37], v[36:37], v[8:9], v[52:53]
	v_pk_mul_f32 v[8:9], v[10:11], v[28:29] op_sel_hi:[1,0]
	s_waitcnt vmcnt(6)
	v_pk_fma_f32 v[12:13], v[40:41], v[12:13], v[56:57]
	v_pk_mul_f32 v[14:15], v[42:43], v[14:15]
	v_pk_add_f32 v[40:41], v[50:51], 1.0 op_sel_hi:[1,0]
	v_pk_mul_f32 v[8:9], v[38:39], v[8:9]
	v_pk_add_f32 v[10:11], v[46:47], 1.0 op_sel_hi:[1,0]
	v_pk_fma_f32 v[14:15], v[40:41], v[14:15], v[58:59]
	v_pk_fma_f32 v[38:39], v[10:11], v[8:9], v[54:55]
	v_cvt_pk_bf16_f32 v8, v12, v13
	v_cvt_pk_bf16_f32 v9, v14, v15
	v_cvt_pk_bf16_f32 v10, v36, v37
	v_cvt_pk_bf16_f32 v11, v38, v39
	global_store_dwordx4 v[24:25], v[8:11], off
	s_waitcnt vmcnt(6)
	v_pk_mul_f32 v[0:1], v[0:1], v[60:61]
	s_waitcnt vmcnt(5)
	v_pk_mul_f32 v[4:5], v[64:65], v[4:5]
	s_waitcnt vmcnt(4)
	v_pk_add_f32 v[60:61], v[68:69], 1.0 op_sel_hi:[1,0]
	s_waitcnt vmcnt(3)
	v_pk_add_f32 v[64:65], v[72:73], 1.0 op_sel_hi:[1,0]
	s_waitcnt vmcnt(2)
	v_pk_fma_f32 v[60:61], v[0:1], v[60:61], v[76:77]
	v_pk_mul_f32 v[0:1], v[2:3], v[28:29] op_sel_hi:[1,0]
	s_waitcnt vmcnt(1)
	v_pk_fma_f32 v[4:5], v[64:65], v[4:5], v[80:81]
	v_pk_mul_f32 v[6:7], v[66:67], v[6:7]
	v_pk_add_f32 v[64:65], v[74:75], 1.0 op_sel_hi:[1,0]
	v_pk_mul_f32 v[0:1], v[0:1], v[62:63]
	v_pk_add_f32 v[2:3], v[70:71], 1.0 op_sel_hi:[1,0]
	v_pk_fma_f32 v[6:7], v[64:65], v[6:7], v[82:83]
	v_pk_fma_f32 v[62:63], v[0:1], v[2:3], v[78:79]
	v_cvt_pk_bf16_f32 v0, v4, v5
	v_cvt_pk_bf16_f32 v1, v6, v7
	v_cvt_pk_bf16_f32 v2, v60, v61
	v_cvt_pk_bf16_f32 v3, v62, v63
	global_store_dwordx4 v[24:25], v[0:3], off offset:1024
	v_lshl_add_u64 v[24:25], v[24:25], 0, s[26:27]
	s_andn2_b64 exec, exec, s[4:5]
	s_cbranch_execnz .LBB0_626
